# attnB: band-mask block skipped when the wave tile is fully inside the window; o kept in place (no per-tile register shuttling), on top of the attnA loop
# speedup vs baseline: 1.0024x; 1.0024x over previous
.LBB0_464:
	s_bitcmp1_b32 s27, 0
	s_cselect_b32 s3, 0x2400, 0
	v_add_u32_e32 v67, s3, v172
	ds_read_b128 v[116:119], v67
	ds_read_b128 v[176:179], v67 offset:4608
	s_cmp_ge_i32 s27, s17
	s_waitcnt lgkmcnt(1)
	v_mfma_f32_32x32x16_bf16 v[100:115], v[116:119], v[132:135], v[84:99]
	v_mov_b64_e32 v[130:131], v[98:99]
	v_mov_b64_e32 v[128:129], v[96:97]
	v_mov_b64_e32 v[126:127], v[94:95]
	v_mov_b64_e32 v[124:125], v[92:93]
	v_mov_b64_e32 v[122:123], v[90:91]
	v_mov_b64_e32 v[120:121], v[88:89]
	v_mov_b64_e32 v[118:119], v[86:87]
	v_mov_b64_e32 v[116:117], v[84:85]
	s_waitcnt lgkmcnt(0)
	s_nop 0
	v_mfma_f32_32x32x16_bf16 v[116:131], v[176:179], v[132:135], v[116:131]
	ds_read_b128 v[176:179], v67 offset:32
	s_waitcnt lgkmcnt(0)
	v_mfma_f32_32x32x16_bf16 v[100:115], v[176:179], v[136:139], v[100:115]
	ds_read_b128 v[176:179], v67 offset:4640
	s_waitcnt lgkmcnt(0)
	v_mfma_f32_32x32x16_bf16 v[116:131], v[176:179], v[136:139], v[116:131]
	ds_read_b128 v[176:179], v67 offset:64
	s_waitcnt lgkmcnt(0)
	v_mfma_f32_32x32x16_bf16 v[100:115], v[176:179], v[140:143], v[100:115]
	ds_read_b128 v[176:179], v67 offset:4672
	s_waitcnt lgkmcnt(0)
	v_mfma_f32_32x32x16_bf16 v[116:131], v[176:179], v[140:143], v[116:131]
	ds_read_b128 v[176:179], v67 offset:96
	s_waitcnt lgkmcnt(0)
	v_mfma_f32_32x32x16_bf16 v[100:115], v[176:179], v[144:147], v[100:115]
	ds_read_b128 v[176:179], v67 offset:4704
	s_waitcnt lgkmcnt(0)
	v_mfma_f32_32x32x16_bf16 v[116:131], v[176:179], v[144:147], v[116:131]
	s_cbranch_scc1 .LBB0_466
	v_readfirstlane_b32 s3, v175
	s_nop 3
	s_addk_i32 s3, 0xe2
	s_cmp_lt_u32 s3, 0xa3
	s_cbranch_scc1 .LBB0_466
	v_cmp_lt_u32_e32 vcc, s61, v175
	v_add_u32_e32 v176, 32, v175
	s_nop 5
	v_cndmask_b32_e32 v100, v226, v100, vcc
	v_cmp_lt_u32_e32 vcc, s61, v176
	v_add_u32_e32 v176, 1, v175
	s_nop 0
	v_cndmask_b32_e32 v116, v226, v116, vcc
	v_cmp_lt_u32_e32 vcc, s61, v176
	v_add_u32_e32 v176, 33, v175
	s_nop 0
	v_cndmask_b32_e32 v101, v226, v101, vcc
	v_cmp_lt_u32_e32 vcc, s61, v176
	v_add_u32_e32 v176, 2, v175
	s_nop 0
	v_cndmask_b32_e32 v117, v226, v117, vcc
	v_cmp_lt_u32_e32 vcc, s61, v176
	v_add_u32_e32 v176, 34, v175
	s_nop 0
	v_cndmask_b32_e32 v102, v226, v102, vcc
	v_cmp_lt_u32_e32 vcc, s61, v176
	v_add_u32_e32 v176, 3, v175
	s_nop 0
	v_cndmask_b32_e32 v118, v226, v118, vcc
	v_cmp_lt_u32_e32 vcc, s61, v176
	v_add_u32_e32 v176, 35, v175
	s_nop 0
	v_cndmask_b32_e32 v103, v226, v103, vcc
	v_cmp_lt_u32_e32 vcc, s61, v176
	v_add_u32_e32 v176, 8, v175
	s_nop 0
	v_cndmask_b32_e32 v119, v226, v119, vcc
	v_cmp_lt_u32_e32 vcc, s61, v176
	v_add_u32_e32 v176, 40, v175
	s_nop 0
	v_cndmask_b32_e32 v104, v226, v104, vcc
	v_cmp_lt_u32_e32 vcc, s61, v176
	v_add_u32_e32 v176, 9, v175
	s_nop 0
	v_cndmask_b32_e32 v120, v226, v120, vcc
	v_cmp_lt_u32_e32 vcc, s61, v176
	v_add_u32_e32 v176, 41, v175
	s_nop 0
	v_cndmask_b32_e32 v105, v226, v105, vcc
	v_cmp_lt_u32_e32 vcc, s61, v176
	v_add_u32_e32 v176, 10, v175
	s_nop 0
	v_cndmask_b32_e32 v121, v226, v121, vcc
	v_cmp_lt_u32_e32 vcc, s61, v176
	v_add_u32_e32 v176, 42, v175
	s_nop 0
	v_cndmask_b32_e32 v106, v226, v106, vcc
	v_cmp_lt_u32_e32 vcc, s61, v176
	v_add_u32_e32 v176, 11, v175
	s_nop 0
	v_cndmask_b32_e32 v122, v226, v122, vcc
	v_cmp_lt_u32_e32 vcc, s61, v176
	v_add_u32_e32 v176, 43, v175
	s_nop 0
	v_cndmask_b32_e32 v107, v226, v107, vcc
	v_cmp_lt_u32_e32 vcc, s61, v176
	v_add_u32_e32 v176, 16, v175
	s_nop 0
	v_cndmask_b32_e32 v123, v226, v123, vcc
	v_cmp_lt_u32_e32 vcc, s61, v176
	v_add_u32_e32 v176, 48, v175
	s_nop 0
	v_cndmask_b32_e32 v108, v226, v108, vcc
	v_cmp_lt_u32_e32 vcc, s61, v176
	v_add_u32_e32 v176, 17, v175
	s_nop 0
	v_cndmask_b32_e32 v124, v226, v124, vcc
	v_cmp_lt_u32_e32 vcc, s61, v176
	v_add_u32_e32 v176, 49, v175
	s_nop 0
	v_cndmask_b32_e32 v109, v226, v109, vcc
	v_cmp_lt_u32_e32 vcc, s61, v176
	v_add_u32_e32 v176, 18, v175
	s_nop 0
	v_cndmask_b32_e32 v125, v226, v125, vcc
	v_cmp_lt_u32_e32 vcc, s61, v176
	v_add_u32_e32 v176, 50, v175
	s_nop 0
	v_cndmask_b32_e32 v110, v226, v110, vcc
	v_cmp_lt_u32_e32 vcc, s61, v176
	v_add_u32_e32 v176, 19, v175
	s_nop 0
	v_cndmask_b32_e32 v126, v226, v126, vcc
	v_cmp_lt_u32_e32 vcc, s61, v176
	v_add_u32_e32 v176, 51, v175
	s_nop 0
	v_cndmask_b32_e32 v111, v226, v111, vcc
	v_cmp_lt_u32_e32 vcc, s61, v176
	v_add_u32_e32 v176, 24, v175
	s_nop 0
	v_cndmask_b32_e32 v127, v226, v127, vcc
	v_cmp_lt_u32_e32 vcc, s61, v176
	v_add_u32_e32 v176, 56, v175
	s_nop 0
	v_cndmask_b32_e32 v112, v226, v112, vcc
	v_cmp_lt_u32_e32 vcc, s61, v176
	v_add_u32_e32 v176, 25, v175
	s_nop 0
	v_cndmask_b32_e32 v128, v226, v128, vcc
	v_cmp_lt_u32_e32 vcc, s61, v176
	v_add_u32_e32 v176, 57, v175
	s_nop 0
	v_cndmask_b32_e32 v113, v226, v113, vcc
	v_cmp_lt_u32_e32 vcc, s61, v176
	v_add_u32_e32 v176, 26, v175
	s_nop 0
	v_cndmask_b32_e32 v129, v226, v129, vcc
	v_cmp_lt_u32_e32 vcc, s61, v176
	v_add_u32_e32 v176, 58, v175
	s_nop 0
	v_cndmask_b32_e32 v114, v226, v114, vcc
	v_cmp_lt_u32_e32 vcc, s61, v176
	v_add_u32_e32 v176, 27, v175
	s_nop 0
	v_cndmask_b32_e32 v130, v226, v130, vcc
	v_cmp_lt_u32_e32 vcc, s61, v176
	v_add_u32_e32 v176, 59, v175
	s_nop 0
	v_cndmask_b32_e32 v115, v226, v115, vcc
	v_cmp_lt_u32_e32 vcc, s61, v176
	s_nop 1
	v_cndmask_b32_e32 v131, v226, v131, vcc

.LBB0_467:
	v_exp_f32_e32 v34, v100
	v_exp_f32_e32 v35, v116
	v_exp_f32_e32 v36, v101
	v_exp_f32_e32 v37, v117
	v_exp_f32_e32 v38, v102
	v_exp_f32_e32 v39, v118
	v_exp_f32_e32 v40, v103
	v_exp_f32_e32 v41, v119
	v_exp_f32_e32 v42, v104
	v_exp_f32_e32 v44, v105
	v_exp_f32_e32 v46, v106
	v_exp_f32_e32 v48, v107
	v_cvt_pk_bf16_f32 v104, v34, v36
	v_cvt_pk_bf16_f32 v105, v38, v40
	v_cvt_pk_bf16_f32 v100, v35, v37
	v_cvt_pk_bf16_f32 v101, v39, v41
	ds_read_b128 v[34:37], v67 offset:18432
	ds_read_b128 v[38:41], v67 offset:18464
	v_cvt_pk_bf16_f32 v106, v42, v44
	v_cvt_pk_bf16_f32 v107, v46, v48
	v_exp_f32_e32 v50, v108
	v_exp_f32_e32 v52, v109
	s_waitcnt lgkmcnt(1)
	v_mfma_f32_32x32x16_bf16 v[2:17], v[34:37], v[104:107], v[2:17]
	ds_read_b128 v[34:37], v67 offset:23040
	v_exp_f32_e32 v54, v110
	v_exp_f32_e32 v56, v111
	v_exp_f32_e32 v58, v112
	v_exp_f32_e32 v60, v113
	v_exp_f32_e32 v62, v114
	v_exp_f32_e32 v64, v115
	s_waitcnt lgkmcnt(0)
	v_mfma_f32_32x32x16_bf16 v[18:33], v[34:37], v[104:107], v[18:33]
	ds_read_b128 v[34:37], v67 offset:23072
	v_cvt_pk_bf16_f32 v108, v50, v52
	v_cvt_pk_bf16_f32 v109, v54, v56
	v_cvt_pk_bf16_f32 v110, v58, v60
	v_cvt_pk_bf16_f32 v111, v62, v64
	v_exp_f32_e32 v43, v120
	v_exp_f32_e32 v45, v121
	s_waitcnt lgkmcnt(0)
	v_mfma_f32_32x32x16_bf16 v[18:33], v[34:37], v[108:111], v[18:33]
	ds_read_b128 v[34:37], v67 offset:18496
	v_exp_f32_e32 v47, v122
	v_exp_f32_e32 v49, v123
	v_exp_f32_e32 v51, v124
	v_exp_f32_e32 v53, v125
	v_cvt_pk_bf16_f32 v102, v43, v45
	v_cvt_pk_bf16_f32 v103, v47, v49
	v_mfma_f32_32x32x16_bf16 v[2:17], v[38:41], v[108:111], v[2:17]
	v_cvt_pk_bf16_f32 v112, v51, v53
	ds_read_b128 v[50:53], v67 offset:18528
	v_exp_f32_e32 v55, v126
	v_exp_f32_e32 v57, v127
	v_exp_f32_e32 v59, v128
	v_exp_f32_e32 v61, v129
	v_exp_f32_e32 v63, v130
	s_waitcnt lgkmcnt(1)
	v_mfma_f32_32x32x16_bf16 v[2:17], v[34:37], v[100:103], v[2:17]
	ds_read_b128 v[34:37], v67 offset:23104
	v_exp_f32_e32 v65, v131
	v_cvt_pk_bf16_f32 v113, v55, v57
	v_cvt_pk_bf16_f32 v114, v59, v61
	s_mov_b32 s65, s64
	v_cvt_pk_bf16_f32 v115, v63, v65
	s_mov_b32 s66, s64
	s_waitcnt lgkmcnt(0)
	v_mfma_f32_32x32x16_bf16 v[18:33], v[34:37], v[100:103], v[18:33]
	ds_read_b128 v[54:57], v67 offset:23136
	s_mov_b32 s67, s64
	v_mfma_f32_32x32x16_bf16 v[2:17], v[50:53], v[112:115], v[2:17]
	v_add_u32_e32 v175, 64, v175
	s_and_b64 vcc, exec, s[20:21]
	s_waitcnt lgkmcnt(0)
	v_mfma_f32_32x32x16_bf16 v[18:33], v[54:57], v[112:115], v[18:33]
	v_mov_b64_e32 v[58:59], s[64:65]
	v_mov_b64_e32 v[60:61], s[66:67]
	s_barrier
	s_nop 0
	v_mfma_f32_32x32x16_bf16 v[68:83], v[58:61], v[104:107], v[68:83]
	v_mfma_f32_32x32x16_bf16 v[68:83], v[58:61], v[108:111], v[68:83]
	v_mfma_f32_32x32x16_bf16 v[68:83], v[58:61], v[100:103], v[68:83]
	v_mfma_f32_32x32x16_bf16 v[68:83], v[58:61], v[112:115], v[68:83]
	s_cbranch_vccnz .Lattn_b_exit
	s_mov_b32 s27, s26
	s_branch .LBB0_460
.Lattn_b_exit:
	s_nop 11
	v_mov_b64_e32 v[34:35], v[2:3]
	v_mov_b64_e32 v[36:37], v[4:5]
	v_mov_b64_e32 v[38:39], v[6:7]
	v_mov_b64_e32 v[40:41], v[8:9]
	v_mov_b64_e32 v[42:43], v[10:11]
	v_mov_b64_e32 v[44:45], v[12:13]
	v_mov_b64_e32 v[46:47], v[14:15]
	v_mov_b64_e32 v[48:49], v[16:17]
	v_mov_b64_e32 v[50:51], v[18:19]
	v_mov_b64_e32 v[52:53], v[20:21]
	v_mov_b64_e32 v[54:55], v[22:23]
	v_mov_b64_e32 v[56:57], v[24:25]
	v_mov_b64_e32 v[58:59], v[26:27]
	v_mov_b64_e32 v[60:61], v[28:29]
	v_mov_b64_e32 v[62:63], v[30:31]
	v_mov_b64_e32 v[64:65], v[32:33]
	s_branch .LBB0_449
.LBB0_469:
	v_max_f32_e32 v176, v176, v176
	v_max_f32_e32 v176, 0, v176
	v_exp_f32_e64 v86, -v176
	v_add_f32_e32 v163, v163, v176
	v_xor_b32_e32 v84, 0x80000000, v163
	v_pk_add_f32 v[100:101], v[100:101], v[176:177] op_sel_hi:[1,0] neg_lo:[0,1] neg_hi:[0,1]
	v_pk_add_f32 v[116:117], v[116:117], v[176:177] op_sel_hi:[1,0] neg_lo:[0,1] neg_hi:[0,1]
	v_pk_add_f32 v[102:103], v[102:103], v[176:177] op_sel_hi:[1,0] neg_lo:[0,1] neg_hi:[0,1]
	v_pk_add_f32 v[118:119], v[118:119], v[176:177] op_sel_hi:[1,0] neg_lo:[0,1] neg_hi:[0,1]
	v_pk_add_f32 v[104:105], v[104:105], v[176:177] op_sel_hi:[1,0] neg_lo:[0,1] neg_hi:[0,1]
	v_pk_add_f32 v[120:121], v[120:121], v[176:177] op_sel_hi:[1,0] neg_lo:[0,1] neg_hi:[0,1]
	v_pk_add_f32 v[106:107], v[106:107], v[176:177] op_sel_hi:[1,0] neg_lo:[0,1] neg_hi:[0,1]
	v_pk_add_f32 v[122:123], v[122:123], v[176:177] op_sel_hi:[1,0] neg_lo:[0,1] neg_hi:[0,1]
	v_pk_add_f32 v[108:109], v[108:109], v[176:177] op_sel_hi:[1,0] neg_lo:[0,1] neg_hi:[0,1]
	v_pk_add_f32 v[124:125], v[124:125], v[176:177] op_sel_hi:[1,0] neg_lo:[0,1] neg_hi:[0,1]
	v_pk_add_f32 v[110:111], v[110:111], v[176:177] op_sel_hi:[1,0] neg_lo:[0,1] neg_hi:[0,1]
	v_pk_add_f32 v[126:127], v[126:127], v[176:177] op_sel_hi:[1,0] neg_lo:[0,1] neg_hi:[0,1]
	v_pk_add_f32 v[112:113], v[112:113], v[176:177] op_sel_hi:[1,0] neg_lo:[0,1] neg_hi:[0,1]
	v_pk_add_f32 v[128:129], v[128:129], v[176:177] op_sel_hi:[1,0] neg_lo:[0,1] neg_hi:[0,1]
	v_pk_add_f32 v[114:115], v[114:115], v[176:177] op_sel_hi:[1,0] neg_lo:[0,1] neg_hi:[0,1]
	v_pk_add_f32 v[130:131], v[130:131], v[176:177] op_sel_hi:[1,0] neg_lo:[0,1] neg_hi:[0,1]
	v_pk_mul_f32 v[32:33], v[32:33], v[86:87] op_sel_hi:[1,0]
	v_pk_mul_f32 v[30:31], v[30:31], v[86:87] op_sel_hi:[1,0]
	v_pk_mul_f32 v[28:29], v[28:29], v[86:87] op_sel_hi:[1,0]
	v_pk_mul_f32 v[26:27], v[26:27], v[86:87] op_sel_hi:[1,0]
	v_pk_mul_f32 v[24:25], v[24:25], v[86:87] op_sel_hi:[1,0]
	v_pk_mul_f32 v[22:23], v[22:23], v[86:87] op_sel_hi:[1,0]
	v_pk_mul_f32 v[20:21], v[20:21], v[86:87] op_sel_hi:[1,0]
	v_pk_mul_f32 v[18:19], v[18:19], v[86:87] op_sel_hi:[1,0]
	v_pk_mul_f32 v[16:17], v[16:17], v[86:87] op_sel_hi:[1,0]
	v_pk_mul_f32 v[14:15], v[14:15], v[86:87] op_sel_hi:[1,0]
	v_pk_mul_f32 v[12:13], v[12:13], v[86:87] op_sel_hi:[1,0]
	v_pk_mul_f32 v[10:11], v[10:11], v[86:87] op_sel_hi:[1,0]
	v_pk_mul_f32 v[8:9], v[8:9], v[86:87] op_sel_hi:[1,0]
	v_pk_mul_f32 v[6:7], v[6:7], v[86:87] op_sel_hi:[1,0]
	v_pk_mul_f32 v[4:5], v[4:5], v[86:87] op_sel_hi:[1,0]
	v_pk_mul_f32 v[2:3], v[2:3], v[86:87] op_sel_hi:[1,0]
	v_pk_mul_f32 v[82:83], v[82:83], v[86:87] op_sel_hi:[1,0]
	v_pk_mul_f32 v[80:81], v[80:81], v[86:87] op_sel_hi:[1,0]
	v_pk_mul_f32 v[78:79], v[78:79], v[86:87] op_sel_hi:[1,0]
	v_pk_mul_f32 v[76:77], v[76:77], v[86:87] op_sel_hi:[1,0]
	v_pk_mul_f32 v[74:75], v[74:75], v[86:87] op_sel_hi:[1,0]
	v_pk_mul_f32 v[72:73], v[72:73], v[86:87] op_sel_hi:[1,0]
	v_pk_mul_f32 v[70:71], v[70:71], v[86:87] op_sel_hi:[1,0]
	v_pk_mul_f32 v[68:69], v[68:69], v[86:87] op_sel_hi:[1,0]
	v_mov_b32_e32 v85, v84
	v_mov_b32_e32 v86, v84
	v_mov_b32_e32 v87, v84
	v_mov_b32_e32 v88, v84
	v_mov_b32_e32 v89, v84
	v_mov_b32_e32 v90, v84
	v_mov_b32_e32 v91, v84
	v_mov_b32_e32 v92, v84
	v_mov_b32_e32 v93, v84
	v_mov_b32_e32 v94, v84
	v_mov_b32_e32 v95, v84
	v_mov_b32_e32 v96, v84
	v_mov_b32_e32 v97, v84
	v_mov_b32_e32 v98, v84
	v_mov_b32_e32 v99, v84
	s_branch .LBB0_467
